# phase-0 layer-0 weight transposes split around the table generation: tile loads (3 per workgroup, workgroups 0..319) issued before it, LDS transpose + bf16 stores after it, so the HBM latency overlaps
# speedup vs baseline: 1.0037x; 1.0014x over previous
.LBB0_33:
	s_cmpk_gt_u32 s96, 0x13f
	s_cbranch_scc1 .Lpb_done
	s_load_dwordx2 s[24:25], s[0:1], 0x38
	s_load_dwordx2 s[26:27], s[0:1], 0x78
	s_waitcnt lgkmcnt(0)
	s_mov_b32 s23, s96
	s_movk_i32 s4, 0x2c0
	s_cmpk_lt_u32 s23, 0x2c0
	s_cselect_b32 s4, 0x0, s4
	s_add_i32 s23, s23, s4
	s_cmpk_gt_i32 s23, 0x57f
	s_cbranch_scc1 .Lpb_out0
	s_mul_hi_i32 s4, s23, 0x2e8ba2e9
	s_ashr_i32 s4, s4, 7
	s_mul_i32 s6, s4, 0x2c0
	s_sub_i32 s6, s23, s6
	s_mul_i32 s7, s6, 0xba3
	s_lshr_b32 s7, s7, 17
	s_mul_i32 s8, s7, 44
	s_sub_i32 s6, s6, s8
	s_mul_i32 s8, s4, 0xb00000
	s_mul_i32 s9, s7, 0xb0000
	s_add_u32 s8, s8, s9
	s_lshl_b32 s9, s6, 8
	s_add_u32 s8, s8, s9
	s_add_u32 s36, s24, s8
	s_addc_u32 s37, s25, 0
	s_sub_i32 s9, s6, 20
	s_cmp_gt_u32 s9, 15
	s_cbranch_scc1 .Lpb_nr0
	s_and_b32 s16, s6, 3
	s_lshr_b32 s9, s9, 2
	s_lshl_b32 s9, s9, 3
	s_lshr_b32 s9, 0x1d15141c, s9
	s_and_b32 s9, s9, 0xff
	s_lshl_b32 s16, s16, 1
	s_add_i32 s6, s9, s16

.Lpb_dec0:
	v_mad_u32_u24 v72, v22, s40, v0
	s_lshl_b32 s17, s40, 4
	global_load_dwordx4 v[208:211], v72, s[36:37] nt
	s_add_u32 s36, s36, s17
	s_addc_u32 s37, s37, 0
	global_load_dwordx4 v[212:215], v72, s[36:37] nt
	s_add_u32 s36, s36, s17
	s_addc_u32 s37, s37, 0
	global_load_dwordx4 v[216:219], v72, s[36:37] nt
	s_add_u32 s36, s36, s17
	s_addc_u32 s37, s37, 0
	global_load_dwordx4 v[220:223], v72, s[36:37] nt
	s_add_i32 s23, s96, 0x140
	s_movk_i32 s4, 0x2c0
	s_cmpk_lt_u32 s23, 0x2c0
	s_cselect_b32 s4, 0x0, s4
	s_add_i32 s23, s23, s4
	s_cmpk_gt_i32 s23, 0x57f
	s_cbranch_scc1 .Lpb_out1
	s_mul_hi_i32 s4, s23, 0x2e8ba2e9
	s_ashr_i32 s4, s4, 7
	s_mul_i32 s6, s4, 0x2c0
	s_sub_i32 s6, s23, s6
	s_mul_i32 s7, s6, 0xba3
	s_lshr_b32 s7, s7, 17
	s_mul_i32 s8, s7, 44
	s_sub_i32 s6, s6, s8
	s_mul_i32 s8, s4, 0xb00000
	s_mul_i32 s9, s7, 0xb0000
	s_add_u32 s8, s8, s9
	s_lshl_b32 s9, s6, 8
	s_add_u32 s8, s8, s9
	s_add_u32 s42, s24, s8
	s_addc_u32 s43, s25, 0
	s_sub_i32 s9, s6, 20
	s_cmp_gt_u32 s9, 15
	s_cbranch_scc1 .Lpb_nr1
	s_and_b32 s16, s6, 3
	s_lshr_b32 s9, s9, 2
	s_lshl_b32 s9, s9, 3
	s_lshr_b32 s9, 0x1d15141c, s9
	s_and_b32 s9, s9, 0xff
	s_lshl_b32 s16, s16, 1
	s_add_i32 s6, s9, s16

.Lpb_dec1:
	v_mad_u32_u24 v73, v22, s41, v0
	s_lshl_b32 s17, s41, 4
	global_load_dwordx4 v[224:227], v73, s[42:43] nt
	s_add_u32 s42, s42, s17
	s_addc_u32 s43, s43, 0
	global_load_dwordx4 v[228:231], v73, s[42:43] nt
	s_add_u32 s42, s42, s17
	s_addc_u32 s43, s43, 0
	global_load_dwordx4 v[232:235], v73, s[42:43] nt
	s_add_u32 s42, s42, s17
	s_addc_u32 s43, s43, 0
	global_load_dwordx4 v[236:239], v73, s[42:43] nt
	s_add_i32 s23, s96, 0x280
	s_cmpk_gt_u32 s23, 0x3bf
	s_cbranch_scc1 .Lpb_dummy
	s_movk_i32 s4, 0x2c0
	s_cmpk_lt_u32 s23, 0x2c0
	s_cselect_b32 s4, 0x0, s4
	s_add_i32 s23, s23, s4
	s_cmpk_gt_i32 s23, 0x57f
	s_cbranch_scc1 .Lpb_out2
	s_mul_hi_i32 s4, s23, 0x2e8ba2e9
	s_ashr_i32 s4, s4, 7
	s_mul_i32 s6, s4, 0x2c0
	s_sub_i32 s6, s23, s6
	s_mul_i32 s7, s6, 0xba3
	s_lshr_b32 s7, s7, 17
	s_mul_i32 s8, s7, 44
	s_sub_i32 s6, s6, s8
	s_mul_i32 s8, s4, 0xb00000
	s_mul_i32 s9, s7, 0xb0000
	s_add_u32 s8, s8, s9
	s_lshl_b32 s9, s6, 8
	s_add_u32 s8, s8, s9
	s_add_u32 s46, s24, s8
	s_addc_u32 s47, s25, 0
	s_sub_i32 s9, s6, 20
	s_cmp_gt_u32 s9, 15
	s_cbranch_scc1 .Lpb_nr2
	s_and_b32 s16, s6, 3
	s_lshr_b32 s9, s9, 2
	s_lshl_b32 s9, s9, 3
	s_lshr_b32 s9, 0x1d15141c, s9
	s_and_b32 s9, s9, 0xff
	s_lshl_b32 s16, s16, 1
	s_add_i32 s6, s9, s16
.Lpb_nr2:
	s_mul_i32 s8, s4, 0x580000
	s_lshl_b32 s9, s6, 17
	s_add_u32 s8, s8, s9
	s_lshl_b32 s9, s7, 7
	s_add_u32 s8, s8, s9
	s_add_u32 s48, s21, s8
	s_addc_u32 s49, s22, 0
	s_movk_i32 s50, 0x2c00
	s_branch .Lpb_dec2
.Lpb_out2:
	s_add_i32 s6, s23, 0xfffffa80
	s_lshr_b32 s4, s6, 8
	s_bfe_u32 s7, s6, 0x40004
	s_and_b32 s6, s6, 15
	s_lshl_b32 s8, s4, 22
	s_lshl_b32 s9, s7, 18
	s_add_u32 s8, s8, s9
	s_lshl_b32 s9, s6, 8
	s_add_u32 s8, s8, s9
	s_add_u32 s46, s26, s8
	s_addc_u32 s47, s27, 0
	s_lshl_b32 s8, s4, 21
	s_lshl_b32 s9, s6, 17
	s_add_u32 s8, s8, s9
	s_lshl_b32 s9, s7, 7
	s_add_u32 s8, s8, s9
	s_add_u32 s48, s19, s8
	s_addc_u32 s49, s20, 0
	s_movk_i32 s50, 0x1000
	s_branch .Lpb_dec2
.Lpb_dummy:
	s_mov_b32 s46, s24
	s_mov_b32 s47, s25
	s_movk_i32 s50, 0x2c00
	s_mov_b32 s4, 0
	s_branch .Lpb_ldl

.Lpb_ldl:
	v_mad_u32_u24 v78, v22, s50, v0
	s_lshl_b32 s17, s50, 4
	global_load_dwordx4 v[240:243], v78, s[46:47] nt
	s_add_u32 s46, s46, s17
	s_addc_u32 s47, s47, 0
	global_load_dwordx4 v[244:247], v78, s[46:47] nt
	s_add_u32 s46, s46, s17
	s_addc_u32 s47, s47, 0
	global_load_dwordx4 v[88:91], v78, s[46:47] nt
	s_add_u32 s46, s46, s17
	s_addc_u32 s47, s47, 0
	global_load_dwordx4 v[92:95], v78, s[46:47] nt

.LBB0_120:
	s_or_b64 exec, exec, s[8:9]
	s_cmpk_gt_u32 s96, 0x13f
	s_cbranch_scc1 .Lpc_done
	s_load_dwordx2 s[24:25], s[0:1], 0x38
	s_load_dwordx2 s[26:27], s[0:1], 0x78
	s_add_u32 s28, s94, 0xd00000
	s_addc_u32 s29, s95, 0
	s_add_u32 s30, s94, 0x200000
	s_addc_u32 s31, s95, 0
	v_lshrrev_b32_e32 v22, 4, v138
	v_and_b32_e32 v0, 15, v138
	v_lshlrev_b32_e32 v0, 4, v0
	v_and_b32_e32 v2, 3, v138
	v_lshlrev_b32_e32 v24, 4, v2
	v_lshlrev_b32_e32 v2, 5, v2
	v_lshrrev_b32_e32 v23, 2, v138
	v_mul_u32_u24_e32 v24, 0x41, v24
	v_and_b32_e32 v25, -4, v138
	v_lshl_add_u32 v24, v24, 2, v25
	v_mul_u32_u24_e32 v25, 0x104, v22
	v_add_u32_e32 v25, v25, v0
	v_add_u32_e32 v26, 0x1040, v25
	v_add_u32_e32 v27, 0x1048, v25
	v_add_u32_e32 v28, 0x2080, v25
	v_add_u32_e32 v29, 0x2088, v25
	v_add_u32_e32 v30, 0x30c0, v25
	v_add_u32_e32 v31, 0x30c8, v25
	v_add_u32_e32 v83, 0x400, v24
	v_add_u32_e32 v84, 0x800, v24
	v_add_u32_e32 v85, 0xc00, v24
	s_waitcnt lgkmcnt(0)
	v_lshl_add_u32 v82, v23, 11, v2
	s_mov_b32 s4, s96
	s_movk_i32 s86, 0x2c0
	s_cmpk_lt_u32 s4, 0x2c0
	s_cselect_b32 s86, 0x0, s86
	s_add_i32 s4, s4, s86
	s_cmpk_gt_i32 s4, 0x57f
	s_cbranch_scc1 .Lpc_out0
	s_mul_hi_i32 s86, s4, 0x2e8ba2e9
	s_ashr_i32 s86, s86, 7
	s_mul_i32 s87, s86, 0x2c0
	s_sub_i32 s87, s4, s87
	s_mul_i32 s88, s87, 0xba3
	s_lshr_b32 s88, s88, 17
	s_mul_i32 s89, s88, 44
	s_sub_i32 s87, s87, s89
	s_mul_i32 s89, s86, 0xb00000
	s_mul_i32 s90, s88, 0xb0000
	s_add_u32 s89, s89, s90
	s_lshl_b32 s90, s87, 8
	s_add_u32 s89, s89, s90
	s_add_u32 s76, s24, s89
	s_addc_u32 s77, s25, 0
	s_sub_i32 s90, s87, 20
	s_cmp_gt_u32 s90, 15
	s_cbranch_scc1 .Lpc_nr0
	s_and_b32 s91, s87, 3
	s_lshr_b32 s90, s90, 2
	s_lshl_b32 s90, s90, 3
	s_lshr_b32 s90, 0x1d15141c, s90
	s_and_b32 s90, s90, 0xff
	s_lshl_b32 s91, s91, 1
	s_add_i32 s87, s90, s91

.Lpc_out0:
	s_add_i32 s87, s4, 0xfffffa80
	s_lshr_b32 s86, s87, 8
	s_bfe_u32 s88, s87, 0x40004
	s_and_b32 s87, s87, 15
	s_lshl_b32 s89, s86, 22
	s_lshl_b32 s90, s88, 18
	s_add_u32 s89, s89, s90
	s_lshl_b32 s90, s87, 8
	s_add_u32 s89, s89, s90
	s_add_u32 s76, s26, s89
	s_addc_u32 s77, s27, 0
	s_lshl_b32 s89, s86, 21
	s_lshl_b32 s90, s87, 17
	s_add_u32 s89, s89, s90
	s_lshl_b32 s90, s88, 7
	s_add_u32 s89, s89, s90
	s_add_u32 s78, s28, s89
	s_addc_u32 s79, s29, 0
	s_movk_i32 s80, 0x1000
.Lpc_dec0:
	s_add_i32 s4, s96, 0x140
	s_movk_i32 s86, 0x2c0
	s_cmpk_lt_u32 s4, 0x2c0
	s_cselect_b32 s86, 0x0, s86
	s_add_i32 s4, s4, s86
	s_cmpk_gt_i32 s4, 0x57f
	s_cbranch_scc1 .Lpc_out1
	s_mul_hi_i32 s86, s4, 0x2e8ba2e9
	s_ashr_i32 s86, s86, 7
	s_mul_i32 s87, s86, 0x2c0
	s_sub_i32 s87, s4, s87
	s_mul_i32 s88, s87, 0xba3
	s_lshr_b32 s88, s88, 17
	s_mul_i32 s89, s88, 44
	s_sub_i32 s87, s87, s89
	s_mul_i32 s89, s86, 0xb00000
	s_mul_i32 s90, s88, 0xb0000
	s_add_u32 s89, s89, s90
	s_lshl_b32 s90, s87, 8
	s_add_u32 s89, s89, s90
	s_add_u32 s82, s24, s89
	s_addc_u32 s83, s25, 0
	s_sub_i32 s90, s87, 20
	s_cmp_gt_u32 s90, 15
	s_cbranch_scc1 .Lpc_nr1
	s_and_b32 s91, s87, 3
	s_lshr_b32 s90, s90, 2
	s_lshl_b32 s90, s90, 3
	s_lshr_b32 s90, 0x1d15141c, s90
	s_and_b32 s90, s90, 0xff
	s_lshl_b32 s91, s91, 1
	s_add_i32 s87, s90, s91

.Lpc_out1:
	s_add_i32 s87, s4, 0xfffffa80
	s_lshr_b32 s86, s87, 8
	s_bfe_u32 s88, s87, 0x40004
	s_and_b32 s87, s87, 15
	s_lshl_b32 s89, s86, 22
	s_lshl_b32 s90, s88, 18
	s_add_u32 s89, s89, s90
	s_lshl_b32 s90, s87, 8
	s_add_u32 s89, s89, s90
	s_add_u32 s82, s26, s89
	s_addc_u32 s83, s27, 0
	s_lshl_b32 s89, s86, 21
	s_lshl_b32 s90, s87, 17
	s_add_u32 s89, s89, s90
	s_lshl_b32 s90, s88, 7
	s_add_u32 s89, s89, s90
	s_add_u32 s84, s28, s89
	s_addc_u32 s85, s29, 0
	s_movk_i32 s81, 0x1000
.Lpc_dec1:
	s_add_i32 s4, s96, 0x280
	s_cmpk_gt_u32 s4, 0x3bf
	s_cbranch_scc1 .Lpc_dummy
	s_movk_i32 s86, 0x2c0
	s_cmpk_lt_u32 s4, 0x2c0
	s_cselect_b32 s86, 0x0, s86
	s_add_i32 s4, s4, s86
	s_cmpk_gt_i32 s4, 0x57f
	s_cbranch_scc1 .Lpc_out2
	s_mul_hi_i32 s86, s4, 0x2e8ba2e9
	s_ashr_i32 s86, s86, 7
	s_mul_i32 s87, s86, 0x2c0
	s_sub_i32 s87, s4, s87
	s_mul_i32 s88, s87, 0xba3
	s_lshr_b32 s88, s88, 17
	s_mul_i32 s89, s88, 44
	s_sub_i32 s87, s87, s89
	s_mul_i32 s89, s86, 0xb00000
	s_mul_i32 s90, s88, 0xb0000
	s_add_u32 s89, s89, s90
	s_lshl_b32 s90, s87, 8
	s_add_u32 s89, s89, s90
	s_add_u32 s40, s24, s89
	s_addc_u32 s41, s25, 0
	s_sub_i32 s90, s87, 20
	s_cmp_gt_u32 s90, 15
	s_cbranch_scc1 .Lpc_nr2
	s_and_b32 s91, s87, 3
	s_lshr_b32 s90, s90, 2
	s_lshl_b32 s90, s90, 3
	s_lshr_b32 s90, 0x1d15141c, s90
	s_and_b32 s90, s90, 0xff
	s_lshl_b32 s91, s91, 1
	s_add_i32 s87, s90, s91
.Lpc_nr2:
	s_mul_i32 s89, s86, 0x580000
	s_lshl_b32 s90, s87, 17
	s_add_u32 s89, s89, s90
	s_lshl_b32 s90, s88, 7
	s_add_u32 s89, s89, s90
	s_add_u32 s44, s30, s89
	s_addc_u32 s45, s31, 0
	s_movk_i32 s42, 0x2c00
	s_branch .Lpc_dec2
.Lpc_out2:
	s_add_i32 s87, s4, 0xfffffa80
	s_lshr_b32 s86, s87, 8
	s_bfe_u32 s88, s87, 0x40004
	s_and_b32 s87, s87, 15
	s_lshl_b32 s89, s86, 22
	s_lshl_b32 s90, s88, 18
	s_add_u32 s89, s89, s90
	s_lshl_b32 s90, s87, 8
	s_add_u32 s89, s89, s90
	s_add_u32 s40, s26, s89
	s_addc_u32 s41, s27, 0
	s_lshl_b32 s89, s86, 21
	s_lshl_b32 s90, s87, 17
	s_add_u32 s89, s89, s90
	s_lshl_b32 s90, s88, 7
	s_add_u32 s89, s89, s90
	s_add_u32 s44, s28, s89
	s_addc_u32 s45, s29, 0
	s_movk_i32 s42, 0x1000
	s_branch .Lpc_dec2
.Lpc_dummy:
	s_mov_b32 s40, s24
	s_mov_b32 s41, s25
	s_movk_i32 s42, 0x2c00
	s_mov_b32 s3, 0
	s_branch .Lpc_ldl

.Lpc_ldl:
	s_waitcnt vmcnt(0)
	s_barrier
	ds_write2_b32 v25, v208, v209 offset1:1
	ds_write2_b32 v25, v210, v211 offset0:2 offset1:3
	ds_write2_b32 v26, v212, v213 offset1:1
	ds_write2_b32 v27, v214, v215 offset1:1
	ds_write2_b32 v28, v216, v217 offset1:1
	ds_write2_b32 v29, v218, v219 offset1:1
	ds_write2_b32 v30, v220, v221 offset1:1
	ds_write2_b32 v31, v222, v223 offset1:1
	s_waitcnt lgkmcnt(0)
	s_barrier
	ds_read2_b32 v[4:5], v24 offset1:65
	ds_read2_b32 v[6:7], v24 offset0:130 offset1:195
	ds_read2_b32 v[8:9], v83 offset0:4 offset1:69
	ds_read2_b32 v[10:11], v83 offset0:134 offset1:199
	ds_read2_b32 v[12:13], v84 offset0:8 offset1:73
	ds_read2_b32 v[14:15], v84 offset0:138 offset1:203
	ds_read2_b32 v[16:17], v85 offset0:12 offset1:77
	ds_read2_b32 v[18:19], v85 offset0:142 offset1:207
	s_waitcnt lgkmcnt(7)
	v_cvt_pk_bf16_f32 v4, v4, v5
	s_waitcnt lgkmcnt(6)
	v_cvt_pk_bf16_f32 v5, v6, v7
	s_waitcnt lgkmcnt(5)
	v_cvt_pk_bf16_f32 v6, v8, v9
	s_waitcnt lgkmcnt(4)
	v_cvt_pk_bf16_f32 v7, v10, v11
	s_waitcnt lgkmcnt(3)
	v_cvt_pk_bf16_f32 v8, v12, v13
	s_waitcnt lgkmcnt(2)
	v_cvt_pk_bf16_f32 v9, v14, v15
	s_waitcnt lgkmcnt(1)
	v_cvt_pk_bf16_f32 v10, v16, v17
	s_waitcnt lgkmcnt(0)
	v_cvt_pk_bf16_f32 v11, v18, v19
	global_store_dwordx4 v82, v[4:7], s[78:79]
	global_store_dwordx4 v82, v[8:11], s[78:79] offset:16
	s_barrier
	ds_write2_b32 v25, v224, v225 offset1:1
	ds_write2_b32 v25, v226, v227 offset0:2 offset1:3
	ds_write2_b32 v26, v228, v229 offset1:1
	ds_write2_b32 v27, v230, v231 offset1:1
	ds_write2_b32 v28, v232, v233 offset1:1
	ds_write2_b32 v29, v234, v235 offset1:1
	ds_write2_b32 v30, v236, v237 offset1:1
	ds_write2_b32 v31, v238, v239 offset1:1
	s_waitcnt lgkmcnt(0)
	s_barrier
	ds_read2_b32 v[4:5], v24 offset1:65
	ds_read2_b32 v[6:7], v24 offset0:130 offset1:195
	ds_read2_b32 v[8:9], v83 offset0:4 offset1:69
	ds_read2_b32 v[10:11], v83 offset0:134 offset1:199
	ds_read2_b32 v[12:13], v84 offset0:8 offset1:73
	ds_read2_b32 v[14:15], v84 offset0:138 offset1:203
	ds_read2_b32 v[16:17], v85 offset0:12 offset1:77
	ds_read2_b32 v[18:19], v85 offset0:142 offset1:207
	s_waitcnt lgkmcnt(7)
	v_cvt_pk_bf16_f32 v4, v4, v5
	s_waitcnt lgkmcnt(6)
	v_cvt_pk_bf16_f32 v5, v6, v7
	s_waitcnt lgkmcnt(5)
	v_cvt_pk_bf16_f32 v6, v8, v9
	s_waitcnt lgkmcnt(4)
	v_cvt_pk_bf16_f32 v7, v10, v11
	s_waitcnt lgkmcnt(3)
	v_cvt_pk_bf16_f32 v8, v12, v13
	s_waitcnt lgkmcnt(2)
	v_cvt_pk_bf16_f32 v9, v14, v15
	s_waitcnt lgkmcnt(1)
	v_cvt_pk_bf16_f32 v10, v16, v17
	s_waitcnt lgkmcnt(0)
	v_cvt_pk_bf16_f32 v11, v18, v19
	global_store_dwordx4 v82, v[4:7], s[84:85]
	global_store_dwordx4 v82, v[8:11], s[84:85] offset:16
	s_cmp_eq_u32 s3, 0
	s_cbranch_scc1 .Lpc_done
	s_barrier
	ds_write2_b32 v25, v240, v241 offset1:1
	ds_write2_b32 v25, v242, v243 offset0:2 offset1:3
	ds_write2_b32 v26, v244, v245 offset1:1
	ds_write2_b32 v27, v246, v247 offset1:1
	ds_write2_b32 v28, v88, v89 offset1:1
	ds_write2_b32 v29, v90, v91 offset1:1
	ds_write2_b32 v30, v92, v93 offset1:1
	ds_write2_b32 v31, v94, v95 offset1:1
	s_waitcnt lgkmcnt(0)
	s_barrier
	ds_read2_b32 v[4:5], v24 offset1:65
	ds_read2_b32 v[6:7], v24 offset0:130 offset1:195
	ds_read2_b32 v[8:9], v83 offset0:4 offset1:69
	ds_read2_b32 v[10:11], v83 offset0:134 offset1:199
	ds_read2_b32 v[12:13], v84 offset0:8 offset1:73
	ds_read2_b32 v[14:15], v84 offset0:138 offset1:203
	ds_read2_b32 v[16:17], v85 offset0:12 offset1:77
	ds_read2_b32 v[18:19], v85 offset0:142 offset1:207
	s_waitcnt lgkmcnt(7)
	v_cvt_pk_bf16_f32 v4, v4, v5
	s_waitcnt lgkmcnt(6)
	v_cvt_pk_bf16_f32 v5, v6, v7
	s_waitcnt lgkmcnt(5)
	v_cvt_pk_bf16_f32 v6, v8, v9
	s_waitcnt lgkmcnt(4)
	v_cvt_pk_bf16_f32 v7, v10, v11
	s_waitcnt lgkmcnt(3)
	v_cvt_pk_bf16_f32 v8, v12, v13
	s_waitcnt lgkmcnt(2)
	v_cvt_pk_bf16_f32 v9, v14, v15
	s_waitcnt lgkmcnt(1)
	v_cvt_pk_bf16_f32 v10, v16, v17
	s_waitcnt lgkmcnt(0)
	v_cvt_pk_bf16_f32 v11, v18, v19
	global_store_dwordx4 v82, v[4:7], s[44:45]
	global_store_dwordx4 v82, v[8:11], s[44:45] offset:16
.Lpc_done:
	s_waitcnt vmcnt(0)
	s_waitcnt lgkmcnt(0)
	s_barrier
	s_and_saveexec_b64 s[2:3], s[14:15]
	s_xor_b64 s[2:3], exec, s[2:3]
	s_lshl_b32 s4, s33, 6
	s_mov_b32 s5, 0
	s_or_saveexec_b64 s[2:3], s[2:3]
	v_mov_b64_e32 v[0:1], s[4:5]
	s_xor_b64 exec, exec, s[2:3]
	s_cbranch_execz .LBB0_175
	v_mov_b32_e32 v0, 0x12000
	s_waitcnt vmcnt(0) expcnt(0) lgkmcnt(0)
	ds_read_b32 v2, v0
	v_mov_b32_e32 v0, 0x12004
	ds_read_b32 v0, v0
	s_waitcnt lgkmcnt(1)
	v_cmp_ne_u32_e32 vcc, 0, v2
	s_cbranch_vccnz .LBB0_138
	s_load_dwordx2 s[8:9], s[0:1], 0x98
	s_load_dword s7, s[0:1], 0xa0
	s_add_u32 s4, s94, 0x1000
	s_addc_u32 s5, s95, 0
	s_add_u32 s6, s94, 0x1100
	s_waitcnt lgkmcnt(0)
	s_mul_i32 s18, s9, s8
	s_mul_i32 s18, s18, s7
	s_addc_u32 s7, s95, 0
	s_add_u32 s8, s94, 0x1200
	s_addc_u32 s9, s95, 0
	s_add_u32 s10, s94, 0x1300
	s_addc_u32 s11, s95, 0
	s_mov_b32 s19, 1
	v_mov_b32_e32 v16, 0
	s_branch .LBB0_126
